# grid barrier release flattened: non-leader workgroups poll the cross-XCC generation word directly, per-XCC generation hop removed
# baseline (speedup 1.0000x reference)
.LBB0_1506:
	s_or_b64 exec, exec, s[12:13]
	s_waitcnt vmcnt(0)
	v_readfirstlane_b32 s2, v3
	v_sub_u32_e32 v4, 0, v2
	s_nop 0
	v_add_u32_e32 v3, s2, v1
	v_cvt_f32_u32_e32 v1, v2
	v_rcp_iflag_f32_e32 v1, v1
	s_nop 0
	v_mul_f32_e32 v1, 0x4f7ffffe, v1
	v_cvt_u32_f32_e32 v1, v1
	v_mul_lo_u32 v4, v4, v1
	v_mul_hi_u32 v4, v1, v4
	v_add_u32_e32 v1, v1, v4
	v_mul_hi_u32 v1, v3, v1
	v_mul_lo_u32 v4, v1, v2
	v_sub_u32_e32 v4, v3, v4
	v_cmp_ge_u32_e32 vcc, v4, v2
	v_add_u32_e32 v5, 1, v1
	s_nop 0
	v_cndmask_b32_e32 v1, v1, v5, vcc
	v_sub_u32_e32 v5, v4, v2
	v_cndmask_b32_e32 v4, v4, v5, vcc
	v_cmp_ge_u32_e32 vcc, v4, v2
	v_add_u32_e32 v4, 1, v1
	s_nop 0
	v_cndmask_b32_e32 v1, v1, v4, vcc
	v_add_u32_e32 v4, 1, v3
	v_mad_u64_u32 v[2:3], s[10:11], v2, v1, v[2:3]
	v_cmp_ne_u32_e32 vcc, v4, v2
	s_and_saveexec_b64 s[10:11], vcc
	s_xor_b64 s[10:11], exec, s[10:11]
	s_cbranch_execz .LBB0_1511
	global_load_dword v0, v153, s[76:77] sc1
	s_mov_b64 s[12:13], s[76:77]
	s_waitcnt vmcnt(0)
	v_cmp_eq_u32_e32 vcc, v0, v1
	s_and_saveexec_b64 s[14:15], vcc
	s_cbranch_execz .LBB0_1510
	s_mov_b64 s[16:17], 0

.LBB0_1523:
	s_or_b64 exec, exec, s[10:11]
	s_mov_b64 s[10:11], exec
	v_mbcnt_lo_u32_b32 v0, s10, 0
	v_mbcnt_hi_u32_b32 v0, s11, v0
	v_cmp_eq_u32_e32 vcc, 0, v0
	s_waitcnt vmcnt(0)
	buffer_inv sc1
	s_waitcnt vmcnt(0)
